# P.V chains: the refill reads of each buffer issued right behind the MFMA that consumed it (reads interleaved between the MFMA pair)
# baseline (speedup 1.0000x reference)
; #define LAS __attribute__((address_space(3)))
; #define MFMA32(a, b, c) __builtin_amdgcn_mfma_f32_32x32x16_bf16((a), (b), (c), 0, 0, 0)
; template <int MODE>
; DI void attn_unit(LAS unsigned char* lds, const bf16_t* Qg, int ldq, const bf16_t* Kg, int ldk, const bf16_t* VTg, int ldvt, bf16_t* Og, int ldo,
;                   int q0, int NT, const float* gout, const float* relb, float lam, float osc, const float* qgain) {
;     ...
;     auto pvdo = [&](const int vbi, const u32x4 (&pp)[4]) {
;         const LAS unsigned char* Vb = lds + VB0 + vbi * VBSZ + (r32 + (MODE == 2 ? mm * 64 : 0)) * VSTR + hi * 8;
; #pragma unroll
;         for (int d = 0; d < NDB; ++d)
; #pragma unroll
;             for (int ks = 0; ks < 4; ++ks) { const int kb = 32 * (ks >> 1) + 16 * (ks & 1);
;                 const s16x4 lo = *(const LAS s16x4*)(Vb + d * 32 * VSTR + kb * 2), hh = *(const LAS s16x4*)(Vb + d * 32 * VSTR + kb * 2 + 16);
;                 const bf16x8 vf = __builtin_shufflevector(lo, hh, 0, 1, 2, 3, 4, 5, 6, 7);
;                 o[d] = MFMA32(vf, __builtin_bit_cast(bf16x8, pp[ks]), o[d]); }
;     };
;     ...
;         if (skew && t >= 1 && (t - 1) < ntw) pvdo(vprev, pk);
.LBB0_188:
	s_add_i32 s2, s15, -1
	s_cmp_le_u32 s2, s18
	s_cselect_b64 s[10:11], -1, 0
	s_and_b64 s[10:11], s[0:1], s[10:11]
	s_andn2_b64 vcc, exec, s[10:11]
	s_cbranch_vccnz .LBB0_190
	s_mul_i32 s3, s13, 0x4400
	s_addk_i32 s3, 0xbc00
	s_cmp_lg_u32 s13, 0
	s_cselect_b32 s3, s3, 0x8800
	v_add_u32_e32 v0, s3, v67
	v_add_u32_e32 v236, 0x8800, v0
	v_add_u32_e32 v237, 0x9800, v0
	v_add_u32_e32 v238, 0xa800, v0
	v_add_u32_e32 v239, 0xb800, v0
	ds_read_b64 v[212:213], v236
	ds_read_b64 v[214:215], v236 offset:16
	ds_read_b64 v[216:217], v236 offset:32
	ds_read_b64 v[218:219], v236 offset:48
	ds_read_b64 v[220:221], v236 offset:64
	ds_read_b64 v[222:223], v236 offset:80
	ds_read_b64 v[224:225], v236 offset:96
	ds_read_b64 v[226:227], v236 offset:112
	s_waitcnt lgkmcnt(4)
	v_mfma_f32_32x32x16_bf16 v[50:65], v[212:215], v[96:99], v[50:65]
	ds_read_b64 v[212:213], v237 offset:256
	ds_read_b64 v[214:215], v237 offset:272
	v_mfma_f32_32x32x16_bf16 v[50:65], v[216:219], v[92:95], v[50:65]
	ds_read_b64 v[216:217], v237 offset:288
	ds_read_b64 v[218:219], v237 offset:304
	s_waitcnt lgkmcnt(4)
	v_mfma_f32_32x32x16_bf16 v[50:65], v[220:223], v[88:91], v[50:65]
	ds_read_b64 v[220:221], v237 offset:320
	ds_read_b64 v[222:223], v237 offset:336
	v_mfma_f32_32x32x16_bf16 v[50:65], v[224:227], v[84:87], v[50:65]
	ds_read_b64 v[224:225], v237 offset:352
	ds_read_b64 v[226:227], v237 offset:368
	s_waitcnt lgkmcnt(4)
	v_mfma_f32_32x32x16_bf16 v[34:49], v[212:215], v[96:99], v[34:49]
	ds_read_b64 v[212:213], v238 offset:512
	ds_read_b64 v[214:215], v238 offset:528
	v_mfma_f32_32x32x16_bf16 v[34:49], v[216:219], v[92:95], v[34:49]
	ds_read_b64 v[216:217], v238 offset:544
	ds_read_b64 v[218:219], v238 offset:560
	s_waitcnt lgkmcnt(4)
	v_mfma_f32_32x32x16_bf16 v[34:49], v[220:223], v[88:91], v[34:49]
	ds_read_b64 v[220:221], v238 offset:576
	ds_read_b64 v[222:223], v238 offset:592
	v_mfma_f32_32x32x16_bf16 v[34:49], v[224:227], v[84:87], v[34:49]
	ds_read_b64 v[224:225], v238 offset:608
	ds_read_b64 v[226:227], v238 offset:624
	s_waitcnt lgkmcnt(4)
	v_mfma_f32_32x32x16_bf16 v[18:33], v[212:215], v[96:99], v[18:33]
	ds_read_b64 v[212:213], v239 offset:768
	ds_read_b64 v[214:215], v239 offset:784
	v_mfma_f32_32x32x16_bf16 v[18:33], v[216:219], v[92:95], v[18:33]
	ds_read_b64 v[216:217], v239 offset:800
	ds_read_b64 v[218:219], v239 offset:816
	s_waitcnt lgkmcnt(4)
	v_mfma_f32_32x32x16_bf16 v[18:33], v[220:223], v[88:91], v[18:33]
	ds_read_b64 v[220:221], v239 offset:832
	ds_read_b64 v[222:223], v239 offset:848
	v_mfma_f32_32x32x16_bf16 v[18:33], v[224:227], v[84:87], v[18:33]
	ds_read_b64 v[224:225], v239 offset:864
	ds_read_b64 v[226:227], v239 offset:880
	s_waitcnt lgkmcnt(4)
	v_mfma_f32_32x32x16_bf16 v[2:17], v[212:215], v[96:99], v[2:17]
	v_mfma_f32_32x32x16_bf16 v[2:17], v[216:219], v[92:95], v[2:17]
	s_waitcnt lgkmcnt(0)
	v_mfma_f32_32x32x16_bf16 v[2:17], v[220:223], v[88:91], v[2:17]
	v_mfma_f32_32x32x16_bf16 v[2:17], v[224:227], v[84:87], v[2:17]

; #define LAS __attribute__((address_space(3)))
; template <int MODE>
; DI void attn_unit(LAS unsigned char* lds, const bf16_t* Qg, int ldq, const bf16_t* Kg, int ldk, const bf16_t* VTg, int ldvt, bf16_t* Og, int ldo,
;                   int q0, int NT, const float* gout, const float* relb, float lam, float osc, const float* qgain) {
;     ...
;     auto pvdo = [&](const int vbi, const u32x4 (&pp)[4]) {
;         const LAS unsigned char* Vb = lds + VB0 + vbi * VBSZ + (r32 + (MODE == 2 ? mm * 64 : 0)) * VSTR + hi * 8;
; #pragma unroll
;         for (int d = 0; d < NDB; ++d)
; #pragma unroll
;             for (int ks = 0; ks < 4; ++ks) { const int kb = 32 * (ks >> 1) + 16 * (ks & 1);
;     ...
;                 float rs = 0.f;
; #pragma unroll
;                 for (int i = 0; i < 16; ++i) { p0[i] = ex2(p0[i]); p1[i] = ex2(p1[i]); rs += p0[i] + p1[i]; }
;                 lrun += rs;
;             } else {
;                 f32x16 L0, L1;
;                 const bool diag = (NT - 1 - t) == TD;
;                 sb_prep(p0, L0, key0 + 4 * hi, qrow, diag); sb_prep(p1, L1, key0 + 32 + 4 * hi, qrow, diag);
;                 float own[8], par[8];
; #pragma unroll
;                 for (int g = 0; g < 4; ++g) { own[g] = (L0[4 * g] + L0[4 * g + 1]) + (L0[4 * g + 2] + L0[4 * g + 3]); own[4 + g] = (L1[4 * g] + L1[4 * g + 1]) + (L1[4 * g + 2] + L1[4 * g + 3]); }
; #pragma unroll
;                 for (int g = 0; g < 8; ++g) par[g] = shx(own[g], 32, lane);
;                 float so = 0.f, sp2 = 0.f;
; #pragma unroll
;                 for (int g = 7; g >= 0; --g) {
;                     const float SG = R + so + sp2 + (hi == 0 ? par[g] : 0.f);
;                     float w = 0.f;
; #pragma unroll
;                     for (int e = 3; e >= 0; --e) { const int idx = 4 * (g & 3) + e;
;                         if (g >= 4) { p1[idx] = ex2(p1[idx] + SG + w); w += L1[idx]; } else { p0[idx] = ex2(p0[idx] + SG + w); w += L0[idx]; } }
;                     so += own[g]; sp2 += par[g];
;                 }
;                 R += so + sp2;
;             }
; #pragma unroll
;             for (int j = 0; j < 4; ++j) { pk[0][j] = cvtpk(p0[2 * j], p0[2 * j + 1]); pk[1][j] = cvtpk(p0[8 + 2 * j], p0[8 + 2 * j + 1]);
;                 pk[2][j] = cvtpk(p1[2 * j], p1[2 * j + 1]); pk[3][j] = cvtpk(p1[8 + 2 * j], p1[8 + 2 * j + 1]); }
;             if (!skew) pvdo(vcur, pk);
.LBB0_195:
	v_exp_f32_e32 v179, v84
	v_exp_f32_e32 v196, v100
	v_exp_f32_e32 v0, v85
	v_exp_f32_e32 v178, v101
	v_exp_f32_e32 v175, v86
	v_exp_f32_e32 v177, v102
	v_exp_f32_e32 v174, v87
	v_exp_f32_e32 v176, v103
	v_exp_f32_e32 v171, v88
	v_exp_f32_e32 v173, v104
	v_exp_f32_e32 v170, v89
	v_exp_f32_e32 v172, v105
	v_exp_f32_e32 v167, v90
	v_exp_f32_e32 v169, v106
	v_exp_f32_e32 v166, v91
	v_exp_f32_e32 v168, v107
	v_exp_f32_e32 v163, v92
	v_exp_f32_e32 v165, v108
	v_exp_f32_e32 v162, v93
	v_exp_f32_e32 v164, v109
	v_exp_f32_e32 v109, v94
	v_exp_f32_e32 v195, v110
	v_exp_f32_e32 v108, v95
	v_exp_f32_e32 v110, v111
	v_exp_f32_e32 v105, v96
	v_exp_f32_e32 v107, v112
	v_exp_f32_e32 v104, v97
	v_exp_f32_e32 v106, v113
	v_exp_f32_e32 v101, v98
	v_exp_f32_e32 v103, v114
	v_exp_f32_e32 v100, v99
	v_exp_f32_e32 v102, v115
	v_cvt_pk_bf16_f32 v96, v179, v0
	v_cvt_pk_bf16_f32 v92, v163, v162
	v_cvt_pk_bf16_f32 v88, v196, v178
	v_cvt_pk_bf16_f32 v84, v165, v164
	v_cvt_pk_bf16_f32 v97, v175, v174
	v_cvt_pk_bf16_f32 v93, v109, v108
	v_cvt_pk_bf16_f32 v89, v177, v176
	v_cvt_pk_bf16_f32 v85, v195, v110
	v_cvt_pk_bf16_f32 v98, v171, v170
	v_cvt_pk_bf16_f32 v94, v105, v104
	v_cvt_pk_bf16_f32 v90, v173, v172
	v_cvt_pk_bf16_f32 v86, v107, v106
	v_cvt_pk_bf16_f32 v99, v167, v166
	v_cvt_pk_bf16_f32 v95, v101, v100
	v_cvt_pk_bf16_f32 v91, v169, v168
	s_andn2_b64 vcc, exec, s[6:7]
	v_cvt_pk_bf16_f32 v87, v103, v102
	s_cbranch_vccnz .LBB0_197
	s_mul_i32 s2, s13, 0x4400
	v_add_u32_e32 v240, s2, v67
	v_add_u32_e32 v236, 0x8800, v240
	v_add_u32_e32 v237, 0x9800, v240
	v_add_u32_e32 v238, 0xa800, v240
	v_add_u32_e32 v239, 0xb800, v240
	ds_read_b64 v[212:213], v236
	ds_read_b64 v[214:215], v236 offset:16
	ds_read_b64 v[216:217], v236 offset:32
	ds_read_b64 v[218:219], v236 offset:48
	ds_read_b64 v[220:221], v236 offset:64
	ds_read_b64 v[222:223], v236 offset:80
	ds_read_b64 v[224:225], v236 offset:96
	ds_read_b64 v[226:227], v236 offset:112
	s_waitcnt lgkmcnt(4)
	v_mfma_f32_32x32x16_bf16 v[50:65], v[212:215], v[96:99], v[50:65]
	ds_read_b64 v[212:213], v237 offset:256
	ds_read_b64 v[214:215], v237 offset:272
	v_mfma_f32_32x32x16_bf16 v[50:65], v[216:219], v[92:95], v[50:65]
	ds_read_b64 v[216:217], v237 offset:288
	ds_read_b64 v[218:219], v237 offset:304
	s_waitcnt lgkmcnt(4)
	v_mfma_f32_32x32x16_bf16 v[50:65], v[220:223], v[88:91], v[50:65]
	ds_read_b64 v[220:221], v237 offset:320
	ds_read_b64 v[222:223], v237 offset:336
	v_mfma_f32_32x32x16_bf16 v[50:65], v[224:227], v[84:87], v[50:65]
	ds_read_b64 v[224:225], v237 offset:352
	ds_read_b64 v[226:227], v237 offset:368
	s_waitcnt lgkmcnt(4)
	v_mfma_f32_32x32x16_bf16 v[34:49], v[212:215], v[96:99], v[34:49]
	ds_read_b64 v[212:213], v238 offset:512
	ds_read_b64 v[214:215], v238 offset:528
	v_mfma_f32_32x32x16_bf16 v[34:49], v[216:219], v[92:95], v[34:49]
	ds_read_b64 v[216:217], v238 offset:544
	ds_read_b64 v[218:219], v238 offset:560
	s_waitcnt lgkmcnt(4)
	v_mfma_f32_32x32x16_bf16 v[34:49], v[220:223], v[88:91], v[34:49]
	ds_read_b64 v[220:221], v238 offset:576
	ds_read_b64 v[222:223], v238 offset:592
	v_mfma_f32_32x32x16_bf16 v[34:49], v[224:227], v[84:87], v[34:49]
	ds_read_b64 v[224:225], v238 offset:608
	ds_read_b64 v[226:227], v238 offset:624
	s_waitcnt lgkmcnt(4)
	v_mfma_f32_32x32x16_bf16 v[18:33], v[212:215], v[96:99], v[18:33]
	ds_read_b64 v[212:213], v239 offset:768
	ds_read_b64 v[214:215], v239 offset:784
	v_mfma_f32_32x32x16_bf16 v[18:33], v[216:219], v[92:95], v[18:33]
	ds_read_b64 v[216:217], v239 offset:800
	ds_read_b64 v[218:219], v239 offset:816
	s_waitcnt lgkmcnt(4)
	v_mfma_f32_32x32x16_bf16 v[18:33], v[220:223], v[88:91], v[18:33]
	ds_read_b64 v[220:221], v239 offset:832
	ds_read_b64 v[222:223], v239 offset:848
	v_mfma_f32_32x32x16_bf16 v[18:33], v[224:227], v[84:87], v[18:33]
	ds_read_b64 v[224:225], v239 offset:864
	ds_read_b64 v[226:227], v239 offset:880
	s_waitcnt lgkmcnt(4)
	v_mfma_f32_32x32x16_bf16 v[2:17], v[212:215], v[96:99], v[2:17]
	v_mfma_f32_32x32x16_bf16 v[2:17], v[216:219], v[92:95], v[2:17]
	s_waitcnt lgkmcnt(0)
	v_mfma_f32_32x32x16_bf16 v[2:17], v[220:223], v[88:91], v[2:17]
	v_mfma_f32_32x32x16_bf16 v[2:17], v[224:227], v[84:87], v[2:17]

; #define LAS __attribute__((address_space(3)))
; #define MFMA32(a, b, c) __builtin_amdgcn_mfma_f32_32x32x16_bf16((a), (b), (c), 0, 0, 0)
; template <int MODE>
; DI void attn_unit(LAS unsigned char* lds, const bf16_t* Qg, int ldq, const bf16_t* Kg, int ldk, const bf16_t* VTg, int ldvt, bf16_t* Og, int ldo,
;                   int q0, int NT, const float* gout, const float* relb, float lam, float osc, const float* qgain) {
;     ...
;     auto pvdo = [&](const int vbi, const u32x4 (&pp)[4]) {
;         const LAS unsigned char* Vb = lds + VB0 + vbi * VBSZ + (r32 + (MODE == 2 ? mm * 64 : 0)) * VSTR + hi * 8;
; #pragma unroll
;         for (int d = 0; d < NDB; ++d)
; #pragma unroll
;             for (int ks = 0; ks < 4; ++ks) { const int kb = 32 * (ks >> 1) + 16 * (ks & 1);
;                 const s16x4 lo = *(const LAS s16x4*)(Vb + d * 32 * VSTR + kb * 2), hh = *(const LAS s16x4*)(Vb + d * 32 * VSTR + kb * 2 + 16);
;                 const bf16x8 vf = __builtin_shufflevector(lo, hh, 0, 1, 2, 3, 4, 5, 6, 7);
;                 o[d] = MFMA32(vf, __builtin_bit_cast(bf16x8, pp[ks]), o[d]); }
;     };
;     ...
;         if (skew && t >= 1 && (t - 1) < ntw) pvdo(vprev, pk);
.LBB0_238:
	s_or_b64 exec, exec, s[6:7]
	global_load_dwordx4 v[2:5], v[142:143], off
	s_add_i32 s2, s13, 3
	s_cmp_le_i32 s2, s10
	s_cselect_b64 s[6:7], -1, 0
	s_and_b64 s[6:7], s[0:1], s[6:7]
	s_andn2_b64 vcc, exec, s[6:7]
	s_cbranch_vccnz .LBB0_240
	s_mul_i32 s3, s11, 0x4400
	s_addk_i32 s3, 0xbc00
	s_cmp_lg_u32 s11, 0
	s_cselect_b32 s3, s3, 0x8800
	v_add_u32_e32 v0, s3, v163
	v_add_u32_e32 v236, 0x8800, v0
	v_add_u32_e32 v237, 0x9800, v0
	ds_read_b64 v[212:213], v236
	ds_read_b64 v[214:215], v236 offset:16
	ds_read_b64 v[216:217], v236 offset:32
	ds_read_b64 v[218:219], v236 offset:48
	ds_read_b64 v[220:221], v236 offset:64
	ds_read_b64 v[222:223], v236 offset:80
	ds_read_b64 v[224:225], v236 offset:96
	ds_read_b64 v[226:227], v236 offset:112
	s_waitcnt lgkmcnt(4)
	v_mfma_f32_32x32x16_bf16 v[32:47], v[212:215], v[68:71], v[32:47]
	ds_read_b64 v[212:213], v237 offset:256
	ds_read_b64 v[214:215], v237 offset:272
	v_mfma_f32_32x32x16_bf16 v[32:47], v[216:219], v[64:67], v[32:47]
	ds_read_b64 v[216:217], v237 offset:288
	ds_read_b64 v[218:219], v237 offset:304
	s_waitcnt lgkmcnt(4)
	v_mfma_f32_32x32x16_bf16 v[32:47], v[220:223], v[10:13], v[32:47]
	ds_read_b64 v[220:221], v237 offset:320
	ds_read_b64 v[222:223], v237 offset:336
	v_mfma_f32_32x32x16_bf16 v[32:47], v[224:227], v[6:9], v[32:47]
	ds_read_b64 v[224:225], v237 offset:352
	ds_read_b64 v[226:227], v237 offset:368
	s_waitcnt lgkmcnt(4)
	v_mfma_f32_32x32x16_bf16 v[16:31], v[212:215], v[68:71], v[16:31]
	v_mfma_f32_32x32x16_bf16 v[16:31], v[216:219], v[64:67], v[16:31]
	s_waitcnt lgkmcnt(0)
	v_mfma_f32_32x32x16_bf16 v[16:31], v[220:223], v[10:13], v[16:31]
	v_mfma_f32_32x32x16_bf16 v[16:31], v[224:227], v[6:9], v[16:31]

; #define LAS __attribute__((address_space(3)))
; template <int MODE>
; DI void attn_unit(LAS unsigned char* lds, const bf16_t* Qg, int ldq, const bf16_t* Kg, int ldk, const bf16_t* VTg, int ldvt, bf16_t* Og, int ldo,
;                   int q0, int NT, const float* gout, const float* relb, float lam, float osc, const float* qgain) {
;     ...
;     auto pvdo = [&](const int vbi, const u32x4 (&pp)[4]) {
;         const LAS unsigned char* Vb = lds + VB0 + vbi * VBSZ + (r32 + (MODE == 2 ? mm * 64 : 0)) * VSTR + hi * 8;
; #pragma unroll
;         for (int d = 0; d < NDB; ++d)
; #pragma unroll
;             for (int ks = 0; ks < 4; ++ks) { const int kb = 32 * (ks >> 1) + 16 * (ks & 1);
;     ...
;                 float rs = 0.f;
; #pragma unroll
;                 for (int i = 0; i < 16; ++i) { p0[i] = ex2(p0[i]); p1[i] = ex2(p1[i]); rs += p0[i] + p1[i]; }
;                 lrun += rs;
;             } else {
;                 f32x16 L0, L1;
;                 const bool diag = (NT - 1 - t) == TD;
;                 sb_prep(p0, L0, key0 + 4 * hi, qrow, diag); sb_prep(p1, L1, key0 + 32 + 4 * hi, qrow, diag);
;                 float own[8], par[8];
; #pragma unroll
;                 for (int g = 0; g < 4; ++g) { own[g] = (L0[4 * g] + L0[4 * g + 1]) + (L0[4 * g + 2] + L0[4 * g + 3]); own[4 + g] = (L1[4 * g] + L1[4 * g + 1]) + (L1[4 * g + 2] + L1[4 * g + 3]); }
; #pragma unroll
;                 for (int g = 0; g < 8; ++g) par[g] = shx(own[g], 32, lane);
;                 float so = 0.f, sp2 = 0.f;
; #pragma unroll
;                 for (int g = 7; g >= 0; --g) {
;                     const float SG = R + so + sp2 + (hi == 0 ? par[g] : 0.f);
;                     float w = 0.f;
; #pragma unroll
;                     for (int e = 3; e >= 0; --e) { const int idx = 4 * (g & 3) + e;
;                         if (g >= 4) { p1[idx] = ex2(p1[idx] + SG + w); w += L1[idx]; } else { p0[idx] = ex2(p0[idx] + SG + w); w += L0[idx]; } }
;                     so += own[g]; sp2 += par[g];
;                 }
;                 R += so + sp2;
;             }
; #pragma unroll
;             for (int j = 0; j < 4; ++j) { pk[0][j] = cvtpk(p0[2 * j], p0[2 * j + 1]); pk[1][j] = cvtpk(p0[8 + 2 * j], p0[8 + 2 * j + 1]);
;                 pk[2][j] = cvtpk(p1[2 * j], p1[2 * j + 1]); pk[3][j] = cvtpk(p1[8 + 2 * j], p1[8 + 2 * j + 1]); }
;             if (!skew) pvdo(vcur, pk);
.LBB0_243:
	v_exp_f32_e32 v159, v80
	v_exp_f32_e32 v173, v64
	v_exp_f32_e32 v158, v81
	v_exp_f32_e32 v0, v65
	v_exp_f32_e32 v155, v82
	v_exp_f32_e32 v157, v66
	v_exp_f32_e32 v154, v83
	v_exp_f32_e32 v156, v67
	v_exp_f32_e32 v151, v84
	v_exp_f32_e32 v153, v68
	v_exp_f32_e32 v150, v85
	v_exp_f32_e32 v152, v69
	v_exp_f32_e32 v145, v86
	v_exp_f32_e32 v147, v70
	v_exp_f32_e32 v144, v87
	v_exp_f32_e32 v146, v71
	v_exp_f32_e32 v87, v88
	v_exp_f32_e32 v172, v72
	v_exp_f32_e32 v86, v89
	v_exp_f32_e32 v88, v73
	v_exp_f32_e32 v83, v90
	v_exp_f32_e32 v85, v74
	v_exp_f32_e32 v82, v91
	v_exp_f32_e32 v84, v75
	v_exp_f32_e32 v81, v92
	v_exp_f32_e32 v90, v76
	v_exp_f32_e32 v76, v93
	v_exp_f32_e32 v80, v77
	v_exp_f32_e32 v73, v94
	v_exp_f32_e32 v75, v78
	v_exp_f32_e32 v72, v95
	v_exp_f32_e32 v74, v79
	v_cvt_pk_bf16_f32 v68, v159, v158
	v_cvt_pk_bf16_f32 v64, v87, v86
	v_cvt_pk_bf16_f32 v10, v173, v0
	v_cvt_pk_bf16_f32 v6, v172, v88
	v_cvt_pk_bf16_f32 v69, v155, v154
	v_cvt_pk_bf16_f32 v65, v83, v82
	v_cvt_pk_bf16_f32 v11, v157, v156
	v_cvt_pk_bf16_f32 v7, v85, v84
	v_cvt_pk_bf16_f32 v70, v151, v150
	v_cvt_pk_bf16_f32 v66, v81, v76
	v_cvt_pk_bf16_f32 v12, v153, v152
	v_cvt_pk_bf16_f32 v8, v90, v80
	v_cvt_pk_bf16_f32 v71, v145, v144
	v_cvt_pk_bf16_f32 v67, v73, v72
	v_cvt_pk_bf16_f32 v13, v147, v146
	s_and_b64 vcc, exec, s[42:43]
	v_cvt_pk_bf16_f32 v9, v75, v74
	s_cbranch_vccnz .LBB0_245
	s_mul_i32 s2, s11, 0x4400
	v_add_u32_e32 v240, s2, v163
	v_add_u32_e32 v236, 0x8800, v240
	v_add_u32_e32 v237, 0x9800, v240
	ds_read_b64 v[212:213], v236
	ds_read_b64 v[214:215], v236 offset:16
	ds_read_b64 v[216:217], v236 offset:32
	ds_read_b64 v[218:219], v236 offset:48
	ds_read_b64 v[220:221], v236 offset:64
	ds_read_b64 v[222:223], v236 offset:80
	ds_read_b64 v[224:225], v236 offset:96
	ds_read_b64 v[226:227], v236 offset:112
	s_waitcnt lgkmcnt(4)
	v_mfma_f32_32x32x16_bf16 v[32:47], v[212:215], v[68:71], v[32:47]
	ds_read_b64 v[212:213], v237 offset:256
	ds_read_b64 v[214:215], v237 offset:272
	v_mfma_f32_32x32x16_bf16 v[32:47], v[216:219], v[64:67], v[32:47]
	ds_read_b64 v[216:217], v237 offset:288
	ds_read_b64 v[218:219], v237 offset:304
	s_waitcnt lgkmcnt(4)
	v_mfma_f32_32x32x16_bf16 v[32:47], v[220:223], v[10:13], v[32:47]
	ds_read_b64 v[220:221], v237 offset:320
	ds_read_b64 v[222:223], v237 offset:336
	v_mfma_f32_32x32x16_bf16 v[32:47], v[224:227], v[6:9], v[32:47]
	ds_read_b64 v[224:225], v237 offset:352
	ds_read_b64 v[226:227], v237 offset:368
	s_waitcnt lgkmcnt(4)
	v_mfma_f32_32x32x16_bf16 v[16:31], v[212:215], v[68:71], v[16:31]
	v_mfma_f32_32x32x16_bf16 v[16:31], v[216:219], v[64:67], v[16:31]
	s_waitcnt lgkmcnt(0)
	v_mfma_f32_32x32x16_bf16 v[16:31], v[220:223], v[10:13], v[16:31]
	v_mfma_f32_32x32x16_bf16 v[16:31], v[224:227], v[6:9], v[16:31]
